# fused-norm GEMM phases: row-tile scan skipped (closed form) when the placement flag guarantees the 256-workgroup grid
# baseline (speedup 1.0000x reference)
; template <bool WANT_PN> __device__ __forceinline__ int unit_tile(int M, int N, int G, int c, int i) {
;     const int nM = M / 256, nN = N / 256, nwg = nM * nN; const long L = (long)i * G + c; if (L >= nwg) return -1;
;     int wgid = (int)L; { const int q = nwg / pg8::NXCD, r = nwg % pg8::NXCD, xcd = wgid % pg8::NXCD, off = wgid / pg8::NXCD; wgid = (xcd < r ? xcd * (q + 1) : r * (q + 1) + (xcd - r) * q) + off; }
;     const int nig = pg8::WGM * nN, gid = wgid / nig, fm = gid * pg8::WGM, gsz = (nM - fm) < pg8::WGM ? (nM - fm) : pg8::WGM;
;     return WANT_PN ? (wgid % nig) / gsz : fm + ((wgid % nig) % gsz);
.Lpro_skip_0:
	s_ashr_i32 s48, s22, 31
	s_mov_b32 s49, s22
	s_mov_b32 s50, -1
	s_mov_b32 s4, 16
	v_mov_b64_e32 v[0:1], 0xaff
	s_mov_b64 s[0:1], s[2:3]
	s_mov_b32 s52, -1
	s_mov_b32 s51, -1
	s_mov_b32 s12, -1
	v_readlane_b32 s101, v249, 48
	s_nop 3
	s_cmp_eq_u32 s101, 0
	s_cbranch_scc1 .LBB0_200
	s_and_b32 s50, s2, 7
	s_lshl_b32 s50, s50, 4
	s_bfe_u32 s101, s2, 0x30003
	s_or_b32 s50, s50, s101
	s_add_i32 s52, s50, 8
	s_branch .LBB0_207

; template <bool WANT_PN> __device__ __forceinline__ int unit_tile(int M, int N, int G, int c, int i) {
;     const int nM = M / 256, nN = N / 256, nwg = nM * nN; const long L = (long)i * G + c; if (L >= nwg) return -1;
;     int wgid = (int)L; { const int q = nwg / pg8::NXCD, r = nwg % pg8::NXCD, xcd = wgid % pg8::NXCD, off = wgid / pg8::NXCD; wgid = (xcd < r ? xcd * (q + 1) : r * (q + 1) + (xcd - r) * q) + off; }
;     const int nig = pg8::WGM * nN, gid = wgid / nig, fm = gid * pg8::WGM, gsz = (nM - fm) < pg8::WGM ? (nM - fm) : pg8::WGM;
;     return WANT_PN ? (wgid % nig) / gsz : fm + ((wgid % nig) % gsz);
.Lpro_skip_1:
	s_ashr_i32 s56, s22, 31
	s_mov_b32 s57, s22
	s_mov_b32 s58, -1
	s_mov_b32 s4, 16
	s_waitcnt lgkmcnt(0)
	v_mov_b64_e32 v[0:1], 0x2ff
	s_mov_b64 s[0:1], s[2:3]
	s_mov_b32 s60, -1
	s_mov_b32 s59, -1
	s_mov_b32 s12, -1
	v_readlane_b32 s101, v249, 48
	s_nop 3
	s_cmp_eq_u32 s101, 0
	s_cbranch_scc1 .LBB0_390
	s_and_b32 s58, s2, 7
	s_lshl_b32 s58, s58, 4
	s_bfe_u32 s101, s2, 0x30003
	s_or_b32 s58, s58, s101
	s_add_i32 s60, s58, 8
	s_branch .LBB0_397

; template <bool WANT_PN> __device__ __forceinline__ int unit_tile(int M, int N, int G, int c, int i) {
;     const int nM = M / 256, nN = N / 256, nwg = nM * nN; const long L = (long)i * G + c; if (L >= nwg) return -1;
;     int wgid = (int)L; { const int q = nwg / pg8::NXCD, r = nwg % pg8::NXCD, xcd = wgid % pg8::NXCD, off = wgid / pg8::NXCD; wgid = (xcd < r ? xcd * (q + 1) : r * (q + 1) + (xcd - r) * q) + off; }
;     const int nig = pg8::WGM * nN, gid = wgid / nig, fm = gid * pg8::WGM, gsz = (nM - fm) < pg8::WGM ? (nM - fm) : pg8::WGM;
;     return WANT_PN ? (wgid % nig) / gsz : fm + ((wgid % nig) % gsz);
.Lpro_skip_2:
	s_ashr_i32 s33, s22, 31
	s_mov_b32 s46, s22
	s_mov_b32 s47, -1
	s_mov_b32 s4, 16
	s_waitcnt lgkmcnt(0)
	v_mov_b64_e32 v[0:1], 0xaff
	s_mov_b64 s[0:1], s[2:3]
	s_mov_b32 s49, -1
	s_mov_b32 s48, -1
	s_mov_b32 s12, -1
	v_readlane_b32 s101, v249, 48
	s_nop 3
	s_cmp_eq_u32 s101, 0
	s_cbranch_scc1 .LBB0_786
	s_and_b32 s47, s2, 7
	s_lshl_b32 s47, s47, 4
	s_bfe_u32 s101, s2, 0x30003
	s_or_b32 s47, s47, s101
	s_add_i32 s49, s47, 8
	s_branch .LBB0_793

; template <bool WANT_PN> __device__ __forceinline__ int unit_tile(int M, int N, int G, int c, int i) {
;     const int nM = M / 256, nN = N / 256, nwg = nM * nN; const long L = (long)i * G + c; if (L >= nwg) return -1;
;     int wgid = (int)L; { const int q = nwg / pg8::NXCD, r = nwg % pg8::NXCD, xcd = wgid % pg8::NXCD, off = wgid / pg8::NXCD; wgid = (xcd < r ? xcd * (q + 1) : r * (q + 1) + (xcd - r) * q) + off; }
;     const int nig = pg8::WGM * nN, gid = wgid / nig, fm = gid * pg8::WGM, gsz = (nM - fm) < pg8::WGM ? (nM - fm) : pg8::WGM;
;     return WANT_PN ? (wgid % nig) / gsz : fm + ((wgid % nig) % gsz);
.Lpro_skip_4:
	s_ashr_i32 s33, s22, 31
	s_mov_b32 s44, s22
	s_mov_b32 s12, -1
	s_mov_b32 s4, 16
	s_waitcnt lgkmcnt(0)
	v_mov_b64_e32 v[0:1], 0xaff
	s_mov_b64 s[0:1], s[2:3]
	s_mov_b32 s45, -1
	s_mov_b32 s46, -1
	s_mov_b32 s47, -1
	v_readlane_b32 s101, v249, 48
	s_nop 3
	s_cmp_eq_u32 s101, 0
	s_cbranch_scc1 .LBB0_1716
	s_and_b32 s47, s2, 7
	s_lshl_b32 s47, s47, 4
	s_bfe_u32 s101, s2, 0x30003
	s_or_b32 s47, s47, s101
	s_add_i32 s46, s47, 8
	s_branch .LBB0_1723
